# norm2 (layer 1) token loop: same chunk-load hoist / no per-chunk vmcnt drain; stacked on v103
# speedup vs baseline: 1.0018x; 1.0018x over previous
.LBB0_1889:
	v_ashrrev_i32_e32 v15, 31, v68
	v_lshrrev_b32_e32 v15, 21, v15
	v_add_u32_e32 v15, v68, v15
	v_ashrrev_i32_e32 v15, 11, v15
	v_lshlrev_b32_e32 v17, 8, v15
	v_add3_u32 v22, v68, v17, s38
	v_mul_hi_i32 v15, v22, s39
	v_lshrrev_b32_e32 v19, 31, v15
	v_ashrrev_i32_e32 v15, 9, v15
	v_add_u32_e32 v15, v15, v19
	v_mad_i32_i24 v20, v15, s40, v17
	v_add3_u32 v20, v68, v20, s38
	v_mul_i32_i24_e32 v19, 0xfffff700, v15
	v_cmp_gt_i32_e64 s[6:7], s38, v20
	v_cmp_lt_i32_e32 vcc, s41, v20
	s_and_saveexec_b64 s[0:1], vcc
	s_xor_b64 s[0:1], exec, s[0:1]
	v_lshl_add_u32 v19, v15, 11, v19
	v_add3_u32 v20, v19, v17, v68
	s_or_saveexec_b64 s[0:1], s[0:1]
	v_mov_b64_e32 v[24:25], s[28:29]
	s_xor_b64 exec, exec, s[0:1]
	v_add3_u32 v17, v68, v17, v19
	v_lshlrev_b32_e32 v19, 8, v15
	v_add3_u32 v20, v17, v19, s38
	v_mov_b64_e32 v[24:25], s[16:17]
	s_or_b64 exec, exec, s[0:1]
	v_ashrrev_i32_e32 v21, 31, v20
	v_lshlrev_b64 v[20:21], 12, v[20:21]
	v_lshl_add_u64 v[20:21], v[24:25], 0, v[20:21]
	v_lshl_add_u64 v[20:21], v[20:21], 0, v[12:13]
	global_load_dwordx2 v[50:51], v[20:21], off
	global_load_dwordx2 v[28:29], v[20:21], off offset:512
	global_load_dwordx2 v[24:25], v[20:21], off offset:1024
	global_load_dwordx2 v[26:27], v[20:21], off offset:1536
	v_add_u32_e32 v71, s27, v68
	v_min_i32_e32 v17, 0x7fff, v71
	v_ashrrev_i32_e32 v19, 31, v17
	v_lshrrev_b32_e32 v19, 21, v19
	v_add_u32_e32 v19, v17, v19
	v_ashrrev_i32_e32 v19, 11, v19
	v_lshlrev_b32_e32 v19, 8, v19
	v_add3_u32 v40, v17, v19, s38
	v_mul_hi_i32 v17, v40, s39
	v_lshrrev_b32_e32 v19, 31, v17
	v_ashrrev_i32_e32 v17, 9, v17
	v_add_u32_e32 v41, v17, v19
	v_mad_i32_i24 v17, v41, s40, v40
	v_cmp_gt_i32_e64 s[4:5], s38, v17
	v_cmp_lt_i32_e32 vcc, s41, v17
	s_and_saveexec_b64 s[0:1], vcc
	s_xor_b64 s[0:1], exec, s[0:1]
	v_lshlrev_b32_e32 v19, 11, v41
	v_add3_u32 v20, v19, v17, s43
	s_or_saveexec_b64 s[0:1], s[0:1]
	v_mov_b64_e32 v[30:31], s[28:29]
	s_xor_b64 exec, exec, s[0:1]
	v_lshl_add_u32 v20, v41, 8, v17
	v_mov_b64_e32 v[30:31], s[16:17]
	s_or_b64 exec, exec, s[0:1]
	v_ashrrev_i32_e32 v21, 31, v20
	v_lshlrev_b64 v[20:21], 12, v[20:21]
	v_lshl_add_u64 v[20:21], v[30:31], 0, v[20:21]
	v_lshl_add_u64 v[20:21], v[20:21], 0, v[12:13]
	global_load_dwordx2 v[48:49], v[20:21], off
	global_load_dwordx2 v[46:47], v[20:21], off offset:512
	global_load_dwordx2 v[42:43], v[20:21], off offset:1024
	global_load_dwordx2 v[44:45], v[20:21], off offset:1536
	v_add_u32_e32 v70, s35, v68
	v_min_i32_e32 v17, 0x7fff, v70
	v_ashrrev_i32_e32 v19, 31, v17
	v_lshrrev_b32_e32 v19, 21, v19
	v_add_u32_e32 v19, v17, v19
	v_ashrrev_i32_e32 v19, 11, v19
	v_lshlrev_b32_e32 v19, 8, v19
	v_add3_u32 v30, v17, v19, s38
	v_mul_hi_i32 v17, v30, s39
	v_lshrrev_b32_e32 v19, 31, v17
	v_ashrrev_i32_e32 v17, 9, v17
	v_add_u32_e32 v31, v17, v19
	v_mad_i32_i24 v17, v31, s40, v30
	v_cmp_gt_i32_e64 s[2:3], s38, v17
	v_cmp_lt_i32_e32 vcc, s41, v17
	s_and_saveexec_b64 s[0:1], vcc
	s_xor_b64 s[0:1], exec, s[0:1]
	v_lshlrev_b32_e32 v19, 11, v31
	v_add3_u32 v20, v19, v17, s43
	s_or_saveexec_b64 s[0:1], s[0:1]
	v_mov_b64_e32 v[32:33], s[28:29]
	s_xor_b64 exec, exec, s[0:1]
	v_lshl_add_u32 v20, v31, 8, v17
	v_mov_b64_e32 v[32:33], s[16:17]
	s_or_b64 exec, exec, s[0:1]
	v_ashrrev_i32_e32 v21, 31, v20
	v_lshlrev_b64 v[20:21], 12, v[20:21]
	v_lshl_add_u64 v[20:21], v[32:33], 0, v[20:21]
	v_lshl_add_u64 v[20:21], v[20:21], 0, v[12:13]
	global_load_dwordx2 v[38:39], v[20:21], off
	global_load_dwordx2 v[36:37], v[20:21], off offset:512
	global_load_dwordx2 v[32:33], v[20:21], off offset:1024
	global_load_dwordx2 v[34:35], v[20:21], off offset:1536
	v_add_u32_e32 v69, s74, v68
	v_min_i32_e32 v17, 0x7fff, v69
	v_ashrrev_i32_e32 v19, 31, v17
	v_lshrrev_b32_e32 v19, 21, v19
	v_add_u32_e32 v19, v17, v19
	v_ashrrev_i32_e32 v19, 11, v19
	v_lshlrev_b32_e32 v19, 8, v19
	v_add3_u32 v20, v17, v19, s38
	v_mul_hi_i32 v17, v20, s39
	v_lshrrev_b32_e32 v19, 31, v17
	v_ashrrev_i32_e32 v17, 9, v17
	v_add_u32_e32 v21, v17, v19
	v_mad_i32_i24 v17, v21, s40, v20
	v_cmp_gt_i32_e32 vcc, s38, v17
	v_cmp_lt_i32_e64 s[0:1], s41, v17
	s_and_saveexec_b64 s[46:47], s[0:1]
	s_xor_b64 s[0:1], exec, s[46:47]
	v_lshlrev_b32_e32 v19, 11, v21
	v_add3_u32 v62, v19, v17, s43
	s_or_saveexec_b64 s[0:1], s[0:1]
	v_mov_b64_e32 v[64:65], s[28:29]
	s_xor_b64 exec, exec, s[0:1]
	v_lshl_add_u32 v62, v21, 8, v17
	v_mov_b64_e32 v[64:65], s[16:17]
	s_or_b64 exec, exec, s[0:1]
	v_cndmask_b32_e64 v15, v15, 16, s[6:7]
	v_mul_hi_i32_i24_e32 v53, 0x6000, v15
	v_mul_i32_i24_e32 v52, 0x6000, v15
	v_lshl_add_u64 v[52:53], s[12:13], 0, v[52:53]
	v_lshl_add_u64 v[58:59], v[52:53], 0, s[18:19]
	v_lshl_add_u64 v[56:57], v[52:53], 0, s[20:21]
	v_lshl_add_u64 v[52:53], v[58:59], 0, v[0:1]
	global_load_dwordx4 v[72:75], v[2:3], off
	global_load_dwordx4 v[76:79], v[52:53], off
	v_lshl_add_u64 v[52:53], v[56:57], 0, v[0:1]
	global_load_dwordx4 v[80:83], v[52:53], off
	global_load_dwordx4 v[100:103], v[4:5], off
	v_mov_b32_e32 v136, v14
	v_mov_b32_e32 v137, v1
	v_lshl_add_u64 v[138:139], v[58:59], 0, v[136:137]
	global_load_dwordx4 v[104:107], v[138:139], off
	v_mov_b32_e32 v136, v14
	v_mov_b32_e32 v137, v1
	v_lshl_add_u64 v[138:139], v[56:57], 0, v[136:137]
	global_load_dwordx4 v[108:111], v[138:139], off
	global_load_dwordx4 v[112:115], v[6:7], off
	v_mov_b32_e32 v136, v16
	v_mov_b32_e32 v137, v1
	v_lshl_add_u64 v[138:139], v[58:59], 0, v[136:137]
	global_load_dwordx4 v[116:119], v[138:139], off
	v_mov_b32_e32 v136, v16
	v_mov_b32_e32 v137, v1
	v_lshl_add_u64 v[138:139], v[56:57], 0, v[136:137]
	global_load_dwordx4 v[120:123], v[138:139], off
	global_load_dwordx4 v[124:127], v[8:9], off
	v_mov_b32_e32 v136, v18
	v_mov_b32_e32 v137, v1
	v_lshl_add_u64 v[138:139], v[58:59], 0, v[136:137]
	global_load_dwordx4 v[128:131], v[138:139], off
	v_mov_b32_e32 v136, v18
	v_mov_b32_e32 v137, v1
	v_lshl_add_u64 v[138:139], v[56:57], 0, v[136:137]
	global_load_dwordx4 v[132:135], v[138:139], off
	s_waitcnt vmcnt(0)
	v_and_b32_e32 v86, 0xffff0000, v50
	v_and_b32_e32 v90, 0xffff0000, v28
	v_ashrrev_i32_e32 v63, 31, v62
	v_lshlrev_b32_e32 v84, 16, v50
	v_lshlrev_b32_e32 v89, 16, v29
	v_lshlrev_b32_e32 v88, 16, v28
	v_and_b32_e32 v91, 0xffff0000, v29
	v_lshlrev_b32_e32 v60, 16, v24
	v_and_b32_e32 v50, 0xffff0000, v24
	v_lshlrev_b32_e32 v54, 16, v25
	v_and_b32_e32 v52, 0xffff0000, v25
	v_ashrrev_i32_e32 v23, 31, v22
	v_lshlrev_b64 v[24:25], 12, v[62:63]
	v_mov_b32_e32 v28, v86
	v_mov_b32_e32 v29, v90
	v_lshlrev_b32_e32 v85, 16, v51
	v_and_b32_e32 v87, 0xffff0000, v51
	v_lshlrev_b32_e32 v61, 16, v26
	v_and_b32_e32 v51, 0xffff0000, v26
	v_lshlrev_b32_e32 v55, 16, v27
	v_and_b32_e32 v53, 0xffff0000, v27
	v_mov_b32_e32 v26, v84
	v_mov_b32_e32 v27, v88
	v_lshlrev_b64 v[96:97], 11, v[22:23]
	v_lshl_add_u64 v[22:23], v[64:65], 0, v[24:25]
	v_pk_mul_f32 v[24:25], v[28:29], v[28:29]
	v_mov_b32_e32 v62, v85
	v_mov_b32_e32 v63, v89
	v_pk_mul_f32 v[94:95], v[50:51], v[50:51]
	v_lshl_add_u64 v[64:65], v[22:23], 0, v[12:13]
	v_pk_fma_f32 v[22:23], v[26:27], v[26:27], v[24:25]
	v_mov_b32_e32 v92, v87
	v_mov_b32_e32 v93, v91
	v_pk_fma_f32 v[28:29], v[60:61], v[60:61], v[94:95]
	v_pk_fma_f32 v[22:23], v[62:63], v[62:63], v[22:23]
	v_pk_fma_f32 v[24:25], v[54:55], v[54:55], v[28:29]
	v_pk_fma_f32 v[22:23], v[92:93], v[92:93], v[22:23]
	v_pk_fma_f32 v[24:25], v[52:53], v[52:53], v[24:25]
	v_add_f32_e32 v15, v22, v23
	v_add_f32_e32 v15, v15, v24
	v_add_f32_e32 v15, v15, v25
	s_nop 1
	v_add_f32_dpp v15, v15, v15 quad_perm:[1,0,3,2] row_mask:0xf bank_mask:0xf bound_ctrl:1
	s_nop 1
	v_add_f32_dpp v15, v15, v15 quad_perm:[2,3,0,1] row_mask:0xf bank_mask:0xf bound_ctrl:1
	s_nop 1
	v_add_f32_dpp v15, v15, v15 row_half_mirror row_mask:0xf bank_mask:0xf bound_ctrl:1
	s_nop 1
	v_add_f32_dpp v15, v15, v15 row_mirror row_mask:0xf bank_mask:0xf bound_ctrl:1
	s_nop 0
	v_readlane_b32 s6, v15, 16
	v_readlane_b32 s7, v15, 48
	v_readlane_b32 s0, v15, 0
	v_readlane_b32 s1, v15, 32
	v_mov_b32_e32 v22, s6
	v_mov_b32_e32 v23, s7
	v_pk_add_f32 v[22:23], s[0:1], v[22:23]
	s_nop 0
	v_add_f32_e32 v15, v22, v23
	v_fmamk_f32 v15, v15, 0x3a800000, v66
	v_mul_f32_e32 v17, 0x4b800000, v15
	v_cmp_gt_f32_e64 s[0:1], s44, v15
	global_load_dwordx2 v[28:29], v[64:65], off
	global_load_dwordx2 v[26:27], v[64:65], off offset:512
	global_load_dwordx2 v[22:23], v[64:65], off offset:1024
	global_load_dwordx2 v[24:25], v[64:65], off offset:1536
	v_cndmask_b32_e64 v15, v15, v17, s[0:1]
	v_rsq_f32_e32 v15, v15
	s_nop 0
	v_mul_f32_e32 v17, 0x45800000, v15
	v_cndmask_b32_e64 v92, v15, v17, s[0:1]
	v_pk_mul_f32 v[62:63], v[92:93], v[84:85] op_sel_hi:[0,1]
	v_pk_mul_f32 v[64:65], v[92:93], v[86:87] op_sel_hi:[0,1]
	s_waitcnt lgkmcnt(0)
	v_mov_b32_e32 v84, v72
	v_mov_b32_e32 v85, v74
	v_mov_b32_e32 v74, v73
	v_mov_b32_e32 v72, v76
	v_mov_b32_e32 v73, v78
	v_pk_mul_f32 v[62:63], v[84:85], v[62:63]
	v_pk_mul_f32 v[64:65], v[74:75], v[64:65]
	v_mov_b32_e32 v74, v80
	v_mov_b32_e32 v75, v82
	v_pk_add_f32 v[72:73], v[72:73], 1.0 op_sel_hi:[1,0]
	v_mov_b32_e32 v78, v77
	v_pk_fma_f32 v[62:63], v[72:73], v[62:63], v[74:75]
	v_pk_add_f32 v[72:73], v[78:79], 1.0 op_sel_hi:[1,0]
	v_mov_b32_e32 v82, v81
	v_pk_fma_f32 v[64:65], v[72:73], v[64:65], v[82:83]
	v_and_b32_sdwa v17, v62, v67 dst_sel:DWORD dst_unused:UNUSED_PAD src0_sel:WORD_1 src1_sel:DWORD
	v_add3_u32 v17, v62, v17, s42
	v_and_b32_sdwa v19, v65, v67 dst_sel:DWORD dst_unused:UNUSED_PAD src0_sel:WORD_1 src1_sel:DWORD
	v_and_b32_sdwa v62, v64, v67 dst_sel:DWORD dst_unused:UNUSED_PAD src0_sel:WORD_1 src1_sel:DWORD
	v_and_b32_sdwa v15, v63, v67 dst_sel:DWORD dst_unused:UNUSED_PAD src0_sel:WORD_1 src1_sel:DWORD
	v_add3_u32 v19, v65, v19, s42
	v_add3_u32 v62, v64, v62, s42
	v_add3_u32 v15, v63, v15, s42
	v_and_b32_e32 v19, 0xffff0000, v19
	v_and_b32_e32 v62, 0xffff0000, v62
	v_or_b32_sdwa v63, v19, v15 dst_sel:DWORD dst_unused:UNUSED_PAD src0_sel:DWORD src1_sel:WORD_1
	v_or_b32_sdwa v62, v62, v17 dst_sel:DWORD dst_unused:UNUSED_PAD src0_sel:DWORD src1_sel:WORD_1
	v_lshl_add_u64 v[80:81], v[10:11], 0, v[96:97]
	v_mov_b32_e32 v15, v1
	global_store_dwordx2 v[80:81], v[62:63], off
	v_lshl_add_u64 v[72:73], v[58:59], 0, v[14:15]
	v_lshl_add_u64 v[76:77], v[56:57], 0, v[14:15]
	v_pk_mul_f32 v[82:83], v[92:93], v[88:89] op_sel_hi:[0,1]
	v_pk_mul_f32 v[84:85], v[92:93], v[90:91] op_sel_hi:[0,1]
	v_mov_b32_e32 v17, v1
	v_cmp_gt_i32_e64 s[0:1], s37, v71
	s_waitcnt lgkmcnt(0)
	v_mov_b32_e32 v62, v100
	v_mov_b32_e32 v63, v101
	v_mov_b32_e32 v64, v102
	v_mov_b32_e32 v65, v103
	v_mov_b32_e32 v72, v104
	v_mov_b32_e32 v73, v105
	v_mov_b32_e32 v74, v106
	v_mov_b32_e32 v75, v107
	v_mov_b32_e32 v76, v108
	v_mov_b32_e32 v77, v109
	v_mov_b32_e32 v78, v110
	v_mov_b32_e32 v79, v111
	v_mov_b32_e32 v86, v62
	v_mov_b32_e32 v87, v64
	v_mov_b32_e32 v88, v72
	v_mov_b32_e32 v89, v74
	v_mov_b32_e32 v64, v63
	v_mov_b32_e32 v74, v73
	v_mov_b32_e32 v90, v76
	v_mov_b32_e32 v91, v78
	v_mov_b32_e32 v78, v77
	v_pk_mul_f32 v[62:63], v[82:83], v[86:87]
	v_pk_add_f32 v[72:73], v[88:89], 1.0 op_sel_hi:[1,0]
	v_pk_mul_f32 v[64:65], v[84:85], v[64:65]
	v_pk_add_f32 v[74:75], v[74:75], 1.0 op_sel_hi:[1,0]
	v_pk_fma_f32 v[62:63], v[62:63], v[72:73], v[90:91]
	v_pk_fma_f32 v[64:65], v[64:65], v[74:75], v[78:79]
	v_and_b32_sdwa v19, v63, v67 dst_sel:DWORD dst_unused:UNUSED_PAD src0_sel:WORD_1 src1_sel:DWORD
	v_and_b32_sdwa v73, v65, v67 dst_sel:DWORD dst_unused:UNUSED_PAD src0_sel:WORD_1 src1_sel:DWORD
	v_and_b32_sdwa v74, v64, v67 dst_sel:DWORD dst_unused:UNUSED_PAD src0_sel:WORD_1 src1_sel:DWORD
	v_and_b32_sdwa v72, v62, v67 dst_sel:DWORD dst_unused:UNUSED_PAD src0_sel:WORD_1 src1_sel:DWORD
	v_add3_u32 v19, v63, v19, s42
	v_add3_u32 v63, v65, v73, s42
	v_add3_u32 v64, v64, v74, s42
	v_add3_u32 v62, v62, v72, s42
	v_and_b32_e32 v63, 0xffff0000, v63
	v_and_b32_e32 v64, 0xffff0000, v64
	v_or_b32_sdwa v63, v63, v19 dst_sel:DWORD dst_unused:UNUSED_PAD src0_sel:DWORD src1_sel:WORD_1
	v_or_b32_sdwa v62, v64, v62 dst_sel:DWORD dst_unused:UNUSED_PAD src0_sel:DWORD src1_sel:WORD_1
	global_store_dwordx2 v[80:81], v[62:63], off offset:512
	v_lshl_add_u64 v[72:73], v[58:59], 0, v[16:17]
	v_lshl_add_u64 v[76:77], v[56:57], 0, v[16:17]
	v_mov_b32_e32 v84, v50
	v_mov_b32_e32 v85, v52
	v_mov_b32_e32 v82, v60
	v_mov_b32_e32 v83, v54
	v_pk_mul_f32 v[84:85], v[92:93], v[84:85] op_sel_hi:[0,1]
	v_pk_mul_f32 v[82:83], v[92:93], v[82:83] op_sel_hi:[0,1]
	v_mov_b32_e32 v19, v1
	v_lshl_add_u64 v[58:59], v[58:59], 0, v[18:19]
	v_lshl_add_u64 v[56:57], v[56:57], 0, v[18:19]
	s_waitcnt lgkmcnt(0)
	v_mov_b32_e32 v62, v112
	v_mov_b32_e32 v63, v113
	v_mov_b32_e32 v64, v114
	v_mov_b32_e32 v65, v115
	v_mov_b32_e32 v72, v116
	v_mov_b32_e32 v73, v117
	v_mov_b32_e32 v74, v118
	v_mov_b32_e32 v75, v119
	v_mov_b32_e32 v76, v120
	v_mov_b32_e32 v77, v121
	v_mov_b32_e32 v78, v122
	v_mov_b32_e32 v79, v123
	v_mov_b32_e32 v87, v64
	v_mov_b32_e32 v64, v63
	v_mov_b32_e32 v89, v74
	v_mov_b32_e32 v74, v73
	v_mov_b32_e32 v86, v62
	v_mov_b32_e32 v88, v72
	v_mov_b32_e32 v91, v78
	v_mov_b32_e32 v78, v77
	v_pk_mul_f32 v[64:65], v[84:85], v[64:65]
	v_pk_add_f32 v[74:75], v[74:75], 1.0 op_sel_hi:[1,0]
	v_mov_b32_e32 v90, v76
	v_pk_mul_f32 v[62:63], v[82:83], v[86:87]
	v_pk_add_f32 v[72:73], v[88:89], 1.0 op_sel_hi:[1,0]
	v_pk_fma_f32 v[64:65], v[64:65], v[74:75], v[78:79]
	v_pk_fma_f32 v[62:63], v[62:63], v[72:73], v[90:91]
	v_and_b32_sdwa v54, v65, v67 dst_sel:DWORD dst_unused:UNUSED_PAD src0_sel:WORD_1 src1_sel:DWORD
	v_and_b32_sdwa v60, v64, v67 dst_sel:DWORD dst_unused:UNUSED_PAD src0_sel:WORD_1 src1_sel:DWORD
	v_and_b32_sdwa v50, v63, v67 dst_sel:DWORD dst_unused:UNUSED_PAD src0_sel:WORD_1 src1_sel:DWORD
	v_and_b32_sdwa v52, v62, v67 dst_sel:DWORD dst_unused:UNUSED_PAD src0_sel:WORD_1 src1_sel:DWORD
	v_add3_u32 v54, v65, v54, s42
	v_add3_u32 v60, v64, v60, s42
	v_add3_u32 v52, v62, v52, s42
	v_add3_u32 v50, v63, v50, s42
	v_and_b32_e32 v54, 0xffff0000, v54
	v_and_b32_e32 v60, 0xffff0000, v60
	v_or_b32_sdwa v63, v54, v50 dst_sel:DWORD dst_unused:UNUSED_PAD src0_sel:DWORD src1_sel:WORD_1
	v_or_b32_sdwa v62, v60, v52 dst_sel:DWORD dst_unused:UNUSED_PAD src0_sel:DWORD src1_sel:WORD_1
	global_store_dwordx2 v[80:81], v[62:63], off offset:1024
	v_mov_b32_e32 v54, v61
	v_mov_b32_e32 v52, v51
	v_pk_mul_f32 v[50:51], v[92:93], v[54:55] op_sel_hi:[0,1]
	v_pk_mul_f32 v[52:53], v[92:93], v[52:53] op_sel_hi:[0,1]
	s_waitcnt lgkmcnt(0)
	v_mov_b32_e32 v62, v124
	v_mov_b32_e32 v63, v125
	v_mov_b32_e32 v64, v126
	v_mov_b32_e32 v65, v127
	v_mov_b32_e32 v72, v128
	v_mov_b32_e32 v73, v129
	v_mov_b32_e32 v74, v130
	v_mov_b32_e32 v75, v131
	v_mov_b32_e32 v56, v132
	v_mov_b32_e32 v57, v133
	v_mov_b32_e32 v58, v134
	v_mov_b32_e32 v59, v135
	v_mov_b32_e32 v55, v64
	v_mov_b32_e32 v64, v63
	v_mov_b32_e32 v61, v74
	v_mov_b32_e32 v74, v73
	v_mov_b32_e32 v54, v62
	v_mov_b32_e32 v60, v72
	v_mov_b32_e32 v76, v56
	v_mov_b32_e32 v77, v58
	v_mov_b32_e32 v58, v57
	v_pk_mul_f32 v[52:53], v[52:53], v[64:65]
	v_pk_add_f32 v[56:57], v[74:75], 1.0 op_sel_hi:[1,0]
	v_pk_mul_f32 v[50:51], v[50:51], v[54:55]
	v_pk_add_f32 v[54:55], v[60:61], 1.0 op_sel_hi:[1,0]
	v_pk_fma_f32 v[52:53], v[52:53], v[56:57], v[58:59]
	v_pk_fma_f32 v[50:51], v[50:51], v[54:55], v[76:77]
	v_and_b32_sdwa v56, v53, v67 dst_sel:DWORD dst_unused:UNUSED_PAD src0_sel:WORD_1 src1_sel:DWORD
	v_and_b32_sdwa v57, v52, v67 dst_sel:DWORD dst_unused:UNUSED_PAD src0_sel:WORD_1 src1_sel:DWORD
	v_and_b32_sdwa v54, v51, v67 dst_sel:DWORD dst_unused:UNUSED_PAD src0_sel:WORD_1 src1_sel:DWORD
	v_and_b32_sdwa v55, v50, v67 dst_sel:DWORD dst_unused:UNUSED_PAD src0_sel:WORD_1 src1_sel:DWORD
	v_add3_u32 v53, v53, v56, s42
	v_add3_u32 v52, v52, v57, s42
	v_add3_u32 v50, v50, v55, s42
	v_add3_u32 v51, v51, v54, s42
	v_and_b32_e32 v53, 0xffff0000, v53
	v_and_b32_e32 v52, 0xffff0000, v52
	v_or_b32_sdwa v51, v53, v51 dst_sel:DWORD dst_unused:UNUSED_PAD src0_sel:DWORD src1_sel:WORD_1
	v_or_b32_sdwa v50, v52, v50 dst_sel:DWORD dst_unused:UNUSED_PAD src0_sel:DWORD src1_sel:WORD_1
	global_store_dwordx2 v[80:81], v[50:51], off offset:1536
	s_and_saveexec_b64 s[6:7], s[0:1]
	s_cbranch_execz .LBB0_1888
	v_cndmask_b32_e64 v41, v41, 16, s[4:5]
	v_mul_hi_i32_i24_e32 v55, 0x6000, v41
	v_mul_i32_i24_e32 v54, 0x6000, v41
	v_lshl_add_u64 v[54:55], s[12:13], 0, v[54:55]
	v_lshl_add_u64 v[62:63], v[54:55], 0, s[18:19]
	global_load_dwordx4 v[50:53], v[2:3], off
	v_lshl_add_u64 v[64:65], v[54:55], 0, s[20:21]
	v_lshl_add_u64 v[54:55], v[62:63], 0, v[0:1]
	global_load_dwordx4 v[54:57], v[54:55], off
	v_lshl_add_u64 v[58:59], v[64:65], 0, v[0:1]
	global_load_dwordx4 v[58:61], v[58:59], off
	global_load_dwordx4 v[100:103], v[4:5], off
	v_mov_b32_e32 v136, v14
	v_mov_b32_e32 v137, v1
	v_lshl_add_u64 v[138:139], v[62:63], 0, v[136:137]
	global_load_dwordx4 v[104:107], v[138:139], off
	v_mov_b32_e32 v136, v14
	v_mov_b32_e32 v137, v1
	v_lshl_add_u64 v[138:139], v[64:65], 0, v[136:137]
	global_load_dwordx4 v[108:111], v[138:139], off
	global_load_dwordx4 v[112:115], v[6:7], off
	v_mov_b32_e32 v136, v16
	v_mov_b32_e32 v137, v1
	v_lshl_add_u64 v[138:139], v[62:63], 0, v[136:137]
	global_load_dwordx4 v[116:119], v[138:139], off
	v_mov_b32_e32 v136, v16
	v_mov_b32_e32 v137, v1
	v_lshl_add_u64 v[138:139], v[64:65], 0, v[136:137]
	global_load_dwordx4 v[120:123], v[138:139], off
	global_load_dwordx4 v[124:127], v[8:9], off
	v_mov_b32_e32 v136, v18
	v_mov_b32_e32 v137, v1
	v_lshl_add_u64 v[138:139], v[62:63], 0, v[136:137]
	global_load_dwordx4 v[128:131], v[138:139], off
	v_mov_b32_e32 v136, v18
	v_mov_b32_e32 v137, v1
	v_lshl_add_u64 v[138:139], v[64:65], 0, v[136:137]
	global_load_dwordx4 v[132:135], v[138:139], off
	v_lshlrev_b32_e32 v72, 16, v48
	v_and_b32_e32 v48, 0xffff0000, v48
	v_and_b32_e32 v76, 0xffff0000, v46
	v_lshlrev_b32_e32 v74, 16, v46
	v_lshlrev_b32_e32 v79, 16, v44
	v_and_b32_e32 v81, 0xffff0000, v44
	v_lshlrev_b32_e32 v83, 16, v45
	v_and_b32_e32 v85, 0xffff0000, v45
	v_mov_b32_e32 v44, v48
	v_mov_b32_e32 v45, v76
	v_lshlrev_b32_e32 v73, 16, v49
	v_lshlrev_b32_e32 v75, 16, v47
	v_lshlrev_b32_e32 v78, 16, v42
	v_and_b32_e32 v80, 0xffff0000, v42
	v_lshlrev_b32_e32 v82, 16, v43
	v_and_b32_e32 v84, 0xffff0000, v43
	v_mov_b32_e32 v42, v72
	v_mov_b32_e32 v43, v74
	v_pk_mul_f32 v[44:45], v[44:45], v[44:45]
	v_and_b32_e32 v49, 0xffff0000, v49
	v_and_b32_e32 v77, 0xffff0000, v47
	v_mov_b32_e32 v46, v73
	v_mov_b32_e32 v47, v75
	v_pk_mul_f32 v[88:89], v[80:81], v[80:81]
	v_pk_fma_f32 v[42:43], v[42:43], v[42:43], v[44:45]
	v_mov_b32_e32 v86, v49
	v_mov_b32_e32 v87, v77
	v_pk_fma_f32 v[88:89], v[78:79], v[78:79], v[88:89]
	v_pk_fma_f32 v[42:43], v[46:47], v[46:47], v[42:43]
	v_pk_fma_f32 v[44:45], v[82:83], v[82:83], v[88:89]
	v_pk_fma_f32 v[42:43], v[86:87], v[86:87], v[42:43]
	v_pk_fma_f32 v[44:45], v[84:85], v[84:85], v[44:45]
	v_add_f32_e32 v41, v42, v43
	v_add_f32_e32 v41, v41, v44
	v_add_f32_e32 v41, v41, v45
	s_waitcnt vmcnt(0) lgkmcnt(0)
	v_mov_b32_e32 v46, v50
	v_add_f32_dpp v41, v41, v41 quad_perm:[1,0,3,2] row_mask:0xf bank_mask:0xf bound_ctrl:1
	v_mov_b32_e32 v47, v52
	v_mov_b32_e32 v52, v51
	v_add_f32_dpp v41, v41, v41 quad_perm:[2,3,0,1] row_mask:0xf bank_mask:0xf bound_ctrl:1
	s_nop 1
	v_add_f32_dpp v41, v41, v41 row_half_mirror row_mask:0xf bank_mask:0xf bound_ctrl:1
	s_nop 1
	v_add_f32_dpp v41, v41, v41 row_mirror row_mask:0xf bank_mask:0xf bound_ctrl:1
	s_nop 0
	v_readlane_b32 s4, v41, 16
	v_readlane_b32 s5, v41, 48
	v_readlane_b32 s0, v41, 0
	v_readlane_b32 s1, v41, 32
	v_mov_b32_e32 v42, s4
	v_mov_b32_e32 v43, s5
	v_pk_add_f32 v[42:43], s[0:1], v[42:43]
	s_nop 0
	v_add_f32_e32 v41, v42, v43
	v_fmamk_f32 v41, v41, 0x3a800000, v66
	v_mul_f32_e32 v42, 0x4b800000, v41
	v_cmp_gt_f32_e64 s[0:1], s44, v41
	s_nop 1
	v_cndmask_b32_e64 v41, v41, v42, s[0:1]
	v_rsq_f32_e32 v42, v41
	v_ashrrev_i32_e32 v41, 31, v40
	v_lshlrev_b64 v[40:41], 11, v[40:41]
	v_mul_f32_e32 v43, 0x45800000, v42
	v_cndmask_b32_e64 v86, v42, v43, s[0:1]
	v_pk_mul_f32 v[42:43], v[86:87], v[72:73] op_sel_hi:[0,1]
	v_pk_mul_f32 v[44:45], v[86:87], v[48:49] op_sel_hi:[0,1]
	v_pk_mul_f32 v[42:43], v[46:47], v[42:43]
	v_mov_b32_e32 v47, v56
	v_mov_b32_e32 v56, v55
	v_pk_mul_f32 v[44:45], v[52:53], v[44:45]
	v_mov_b32_e32 v46, v54
	v_mov_b32_e32 v49, v60
	v_mov_b32_e32 v60, v59
	v_pk_add_f32 v[50:51], v[56:57], 1.0 op_sel_hi:[1,0]
	v_mov_b32_e32 v48, v58
	v_pk_add_f32 v[46:47], v[46:47], 1.0 op_sel_hi:[1,0]
	v_pk_fma_f32 v[44:45], v[50:51], v[44:45], v[60:61]
	v_pk_fma_f32 v[42:43], v[46:47], v[42:43], v[48:49]
	v_and_b32_sdwa v48, v45, v67 dst_sel:DWORD dst_unused:UNUSED_PAD src0_sel:WORD_1 src1_sel:DWORD
	v_and_b32_sdwa v49, v44, v67 dst_sel:DWORD dst_unused:UNUSED_PAD src0_sel:WORD_1 src1_sel:DWORD
	v_and_b32_sdwa v46, v43, v67 dst_sel:DWORD dst_unused:UNUSED_PAD src0_sel:WORD_1 src1_sel:DWORD
	v_and_b32_sdwa v47, v42, v67 dst_sel:DWORD dst_unused:UNUSED_PAD src0_sel:WORD_1 src1_sel:DWORD
	v_add3_u32 v45, v45, v48, s42
	v_add3_u32 v44, v44, v49, s42
	v_add3_u32 v42, v42, v47, s42
	v_add3_u32 v43, v43, v46, s42
	v_and_b32_e32 v45, 0xffff0000, v45
	v_and_b32_e32 v44, 0xffff0000, v44
	v_or_b32_sdwa v43, v45, v43 dst_sel:DWORD dst_unused:UNUSED_PAD src0_sel:DWORD src1_sel:WORD_1
	v_or_b32_sdwa v42, v44, v42 dst_sel:DWORD dst_unused:UNUSED_PAD src0_sel:DWORD src1_sel:WORD_1
	v_lshl_add_u64 v[52:53], v[10:11], 0, v[40:41]
	global_store_dwordx2 v[52:53], v[42:43], off
	v_lshl_add_u64 v[44:45], v[62:63], 0, v[14:15]
	v_lshl_add_u64 v[48:49], v[64:65], 0, v[14:15]
	v_pk_mul_f32 v[54:55], v[86:87], v[74:75] op_sel_hi:[0,1]
	v_pk_mul_f32 v[56:57], v[86:87], v[76:77] op_sel_hi:[0,1]
	v_cmp_gt_i32_e64 s[0:1], s37, v70
	s_waitcnt lgkmcnt(0)
	v_mov_b32_e32 v40, v100
	v_mov_b32_e32 v41, v101
	v_mov_b32_e32 v42, v102
	v_mov_b32_e32 v43, v103
	v_mov_b32_e32 v44, v104
	v_mov_b32_e32 v45, v105
	v_mov_b32_e32 v46, v106
	v_mov_b32_e32 v47, v107
	v_mov_b32_e32 v48, v108
	v_mov_b32_e32 v49, v109
	v_mov_b32_e32 v50, v110
	v_mov_b32_e32 v51, v111
	v_mov_b32_e32 v58, v40
	v_mov_b32_e32 v59, v42
	v_mov_b32_e32 v60, v44
	v_mov_b32_e32 v61, v46
	v_mov_b32_e32 v42, v41
	v_mov_b32_e32 v46, v45
	v_mov_b32_e32 v72, v48
	v_mov_b32_e32 v73, v50
	v_mov_b32_e32 v50, v49
	v_pk_mul_f32 v[40:41], v[54:55], v[58:59]
	v_pk_add_f32 v[44:45], v[60:61], 1.0 op_sel_hi:[1,0]
	v_pk_mul_f32 v[42:43], v[56:57], v[42:43]
	v_pk_add_f32 v[46:47], v[46:47], 1.0 op_sel_hi:[1,0]
	v_pk_fma_f32 v[40:41], v[40:41], v[44:45], v[72:73]
	v_pk_fma_f32 v[42:43], v[42:43], v[46:47], v[50:51]
	v_and_b32_sdwa v15, v41, v67 dst_sel:DWORD dst_unused:UNUSED_PAD src0_sel:WORD_1 src1_sel:DWORD
	v_and_b32_sdwa v45, v43, v67 dst_sel:DWORD dst_unused:UNUSED_PAD src0_sel:WORD_1 src1_sel:DWORD
	v_and_b32_sdwa v46, v42, v67 dst_sel:DWORD dst_unused:UNUSED_PAD src0_sel:WORD_1 src1_sel:DWORD
	v_and_b32_sdwa v44, v40, v67 dst_sel:DWORD dst_unused:UNUSED_PAD src0_sel:WORD_1 src1_sel:DWORD
	v_add3_u32 v15, v41, v15, s42
	v_add3_u32 v41, v43, v45, s42
	v_add3_u32 v42, v42, v46, s42
	v_add3_u32 v40, v40, v44, s42
	v_and_b32_e32 v41, 0xffff0000, v41
	v_and_b32_e32 v42, 0xffff0000, v42
	v_or_b32_sdwa v41, v41, v15 dst_sel:DWORD dst_unused:UNUSED_PAD src0_sel:DWORD src1_sel:WORD_1
	v_or_b32_sdwa v40, v42, v40 dst_sel:DWORD dst_unused:UNUSED_PAD src0_sel:DWORD src1_sel:WORD_1
	global_store_dwordx2 v[52:53], v[40:41], off offset:512
	v_lshl_add_u64 v[44:45], v[62:63], 0, v[16:17]
	v_lshl_add_u64 v[48:49], v[64:65], 0, v[16:17]
	v_mov_b32_e32 v54, v78
	v_mov_b32_e32 v55, v82
	v_mov_b32_e32 v56, v80
	v_mov_b32_e32 v57, v84
	v_pk_mul_f32 v[54:55], v[86:87], v[54:55] op_sel_hi:[0,1]
	v_pk_mul_f32 v[56:57], v[86:87], v[56:57] op_sel_hi:[0,1]
	v_mov_b32_e32 v82, v79
	v_mov_b32_e32 v84, v81
	s_waitcnt lgkmcnt(0)
	v_mov_b32_e32 v40, v112
	v_mov_b32_e32 v41, v113
	v_mov_b32_e32 v42, v114
	v_mov_b32_e32 v43, v115
	v_mov_b32_e32 v44, v116
	v_mov_b32_e32 v45, v117
	v_mov_b32_e32 v46, v118
	v_mov_b32_e32 v47, v119
	v_mov_b32_e32 v48, v120
	v_mov_b32_e32 v49, v121
	v_mov_b32_e32 v50, v122
	v_mov_b32_e32 v51, v123
	v_mov_b32_e32 v58, v40
	v_mov_b32_e32 v59, v42
	v_mov_b32_e32 v60, v44
	v_mov_b32_e32 v61, v46
	v_mov_b32_e32 v42, v41
	v_mov_b32_e32 v46, v45
	v_mov_b32_e32 v72, v48
	v_mov_b32_e32 v73, v50
	v_mov_b32_e32 v50, v49
	v_pk_mul_f32 v[40:41], v[54:55], v[58:59]
	v_pk_add_f32 v[44:45], v[60:61], 1.0 op_sel_hi:[1,0]
	v_pk_mul_f32 v[42:43], v[56:57], v[42:43]
	v_pk_add_f32 v[46:47], v[46:47], 1.0 op_sel_hi:[1,0]
	v_pk_fma_f32 v[40:41], v[40:41], v[44:45], v[72:73]
	v_pk_fma_f32 v[42:43], v[42:43], v[46:47], v[50:51]
	v_and_b32_sdwa v15, v41, v67 dst_sel:DWORD dst_unused:UNUSED_PAD src0_sel:WORD_1 src1_sel:DWORD
	v_and_b32_sdwa v17, v40, v67 dst_sel:DWORD dst_unused:UNUSED_PAD src0_sel:WORD_1 src1_sel:DWORD
	v_and_b32_sdwa v44, v43, v67 dst_sel:DWORD dst_unused:UNUSED_PAD src0_sel:WORD_1 src1_sel:DWORD
	v_and_b32_sdwa v45, v42, v67 dst_sel:DWORD dst_unused:UNUSED_PAD src0_sel:WORD_1 src1_sel:DWORD
	v_add3_u32 v17, v40, v17, s42
	v_add3_u32 v15, v41, v15, s42
	v_add3_u32 v40, v43, v44, s42
	v_add3_u32 v41, v42, v45, s42
	v_and_b32_e32 v40, 0xffff0000, v40
	v_and_b32_e32 v42, 0xffff0000, v41
	v_or_b32_sdwa v41, v40, v15 dst_sel:DWORD dst_unused:UNUSED_PAD src0_sel:DWORD src1_sel:WORD_1
	v_or_b32_sdwa v40, v42, v17 dst_sel:DWORD dst_unused:UNUSED_PAD src0_sel:DWORD src1_sel:WORD_1
	global_store_dwordx2 v[52:53], v[40:41], off offset:1024
	v_lshl_add_u64 v[44:45], v[62:63], 0, v[18:19]
	v_lshl_add_u64 v[48:49], v[64:65], 0, v[18:19]
	v_pk_mul_f32 v[54:55], v[86:87], v[82:83] op_sel_hi:[0,1]
	v_pk_mul_f32 v[56:57], v[86:87], v[84:85] op_sel_hi:[0,1]
	s_waitcnt lgkmcnt(0)
	v_mov_b32_e32 v40, v124
	v_mov_b32_e32 v41, v125
	v_mov_b32_e32 v42, v126
	v_mov_b32_e32 v43, v127
	v_mov_b32_e32 v44, v128
	v_mov_b32_e32 v45, v129
	v_mov_b32_e32 v46, v130
	v_mov_b32_e32 v47, v131
	v_mov_b32_e32 v48, v132
	v_mov_b32_e32 v49, v133
	v_mov_b32_e32 v50, v134
	v_mov_b32_e32 v51, v135
	v_mov_b32_e32 v58, v40
	v_mov_b32_e32 v59, v42
	v_mov_b32_e32 v60, v44
	v_mov_b32_e32 v61, v46
	v_mov_b32_e32 v42, v41
	v_mov_b32_e32 v46, v45
	v_mov_b32_e32 v62, v48
	v_mov_b32_e32 v63, v50
	v_mov_b32_e32 v50, v49
	v_pk_mul_f32 v[40:41], v[54:55], v[58:59]
	v_pk_add_f32 v[44:45], v[60:61], 1.0 op_sel_hi:[1,0]
	v_pk_mul_f32 v[42:43], v[56:57], v[42:43]
	v_pk_add_f32 v[46:47], v[46:47], 1.0 op_sel_hi:[1,0]
	v_pk_fma_f32 v[40:41], v[40:41], v[44:45], v[62:63]
	v_pk_fma_f32 v[42:43], v[42:43], v[46:47], v[50:51]
	v_and_b32_sdwa v17, v40, v67 dst_sel:DWORD dst_unused:UNUSED_PAD src0_sel:WORD_1 src1_sel:DWORD
	v_and_b32_sdwa v19, v43, v67 dst_sel:DWORD dst_unused:UNUSED_PAD src0_sel:WORD_1 src1_sel:DWORD
	v_and_b32_sdwa v44, v42, v67 dst_sel:DWORD dst_unused:UNUSED_PAD src0_sel:WORD_1 src1_sel:DWORD
	v_and_b32_sdwa v15, v41, v67 dst_sel:DWORD dst_unused:UNUSED_PAD src0_sel:WORD_1 src1_sel:DWORD
	v_add3_u32 v17, v40, v17, s42
	v_add3_u32 v19, v43, v19, s42
	v_add3_u32 v40, v42, v44, s42
	v_add3_u32 v15, v41, v15, s42
	v_and_b32_e32 v19, 0xffff0000, v19
	v_and_b32_e32 v40, 0xffff0000, v40
	v_or_b32_sdwa v41, v19, v15 dst_sel:DWORD dst_unused:UNUSED_PAD src0_sel:DWORD src1_sel:WORD_1
	v_or_b32_sdwa v40, v40, v17 dst_sel:DWORD dst_unused:UNUSED_PAD src0_sel:DWORD src1_sel:WORD_1
	global_store_dwordx2 v[52:53], v[40:41], off offset:1536
	s_and_b64 exec, exec, s[0:1]
	s_cbranch_execz .LBB0_1888
	v_cndmask_b32_e64 v15, v31, 16, s[2:3]
	v_mul_hi_i32_i24_e32 v41, 0x6000, v15
	v_mul_i32_i24_e32 v40, 0x6000, v15
	v_lshl_add_u64 v[40:41], s[12:13], 0, v[40:41]
	v_lshl_add_u64 v[42:43], v[40:41], 0, s[18:19]
	global_load_dwordx4 v[46:49], v[2:3], off
	v_lshl_add_u64 v[40:41], v[40:41], 0, s[20:21]
	v_lshl_add_u64 v[44:45], v[42:43], 0, v[0:1]
	global_load_dwordx4 v[50:53], v[44:45], off
	v_lshl_add_u64 v[44:45], v[40:41], 0, v[0:1]
	global_load_dwordx4 v[54:57], v[44:45], off
	global_load_dwordx4 v[100:103], v[4:5], off
	v_mov_b32_e32 v136, v14
	v_mov_b32_e32 v137, v1
	v_lshl_add_u64 v[138:139], v[42:43], 0, v[136:137]
	global_load_dwordx4 v[104:107], v[138:139], off
	v_mov_b32_e32 v136, v14
	v_mov_b32_e32 v137, v1
	v_lshl_add_u64 v[138:139], v[40:41], 0, v[136:137]
	global_load_dwordx4 v[108:111], v[138:139], off
	global_load_dwordx4 v[112:115], v[6:7], off
	v_mov_b32_e32 v136, v16
	v_mov_b32_e32 v137, v1
	v_lshl_add_u64 v[138:139], v[42:43], 0, v[136:137]
	global_load_dwordx4 v[116:119], v[138:139], off
	v_mov_b32_e32 v136, v16
	v_mov_b32_e32 v137, v1
	v_lshl_add_u64 v[138:139], v[40:41], 0, v[136:137]
	global_load_dwordx4 v[120:123], v[138:139], off
	global_load_dwordx4 v[124:127], v[8:9], off
	v_mov_b32_e32 v136, v18
	v_mov_b32_e32 v137, v1
	v_lshl_add_u64 v[138:139], v[42:43], 0, v[136:137]
	global_load_dwordx4 v[128:131], v[138:139], off
	v_mov_b32_e32 v136, v18
	v_mov_b32_e32 v137, v1
	v_lshl_add_u64 v[138:139], v[40:41], 0, v[136:137]
	global_load_dwordx4 v[132:135], v[138:139], off
	v_and_b32_e32 v60, 0xffff0000, v38
	v_and_b32_e32 v64, 0xffff0000, v36
	v_lshlrev_b32_e32 v58, 16, v38
	v_lshlrev_b32_e32 v62, 16, v36
	v_mov_b32_e32 v70, v60
	v_mov_b32_e32 v71, v64
	v_lshlrev_b32_e32 v59, 16, v39
	v_lshlrev_b32_e32 v63, 16, v37
	v_and_b32_e32 v65, 0xffff0000, v37
	v_lshlrev_b32_e32 v45, 16, v34
	v_lshlrev_b32_e32 v44, 16, v32
	v_and_b32_e32 v37, 0xffff0000, v34
	v_and_b32_e32 v36, 0xffff0000, v32
	v_lshlrev_b32_e32 v38, 16, v33
	v_and_b32_e32 v34, 0xffff0000, v33
	v_mov_b32_e32 v32, v58
	v_mov_b32_e32 v33, v62
	v_pk_mul_f32 v[70:71], v[70:71], v[70:71]
	v_and_b32_e32 v61, 0xffff0000, v39
	v_mov_b32_e32 v72, v59
	v_mov_b32_e32 v73, v63
	v_pk_mul_f32 v[76:77], v[36:37], v[36:37]
	v_pk_fma_f32 v[32:33], v[32:33], v[32:33], v[70:71]
	v_lshlrev_b32_e32 v39, 16, v35
	v_mov_b32_e32 v74, v61
	v_mov_b32_e32 v75, v65
	v_pk_fma_f32 v[76:77], v[44:45], v[44:45], v[76:77]
	v_pk_fma_f32 v[32:33], v[72:73], v[72:73], v[32:33]
	v_and_b32_e32 v35, 0xffff0000, v35
	v_pk_fma_f32 v[70:71], v[38:39], v[38:39], v[76:77]
	v_pk_fma_f32 v[32:33], v[74:75], v[74:75], v[32:33]
	v_pk_fma_f32 v[70:71], v[34:35], v[34:35], v[70:71]
	v_add_f32_e32 v15, v32, v33
	v_add_f32_e32 v15, v15, v70
	v_add_f32_e32 v15, v15, v71
	v_ashrrev_i32_e32 v31, 31, v30
	v_lshlrev_b64 v[30:31], 11, v[30:31]
	v_add_f32_dpp v15, v15, v15 quad_perm:[1,0,3,2] row_mask:0xf bank_mask:0xf bound_ctrl:1
	s_nop 1
	v_add_f32_dpp v15, v15, v15 quad_perm:[2,3,0,1] row_mask:0xf bank_mask:0xf bound_ctrl:1
	s_nop 1
	v_add_f32_dpp v15, v15, v15 row_half_mirror row_mask:0xf bank_mask:0xf bound_ctrl:1
	s_nop 1
	v_add_f32_dpp v15, v15, v15 row_mirror row_mask:0xf bank_mask:0xf bound_ctrl:1
	s_nop 0
	v_readlane_b32 s2, v15, 16
	v_readlane_b32 s3, v15, 48
	v_readlane_b32 s0, v15, 0
	v_readlane_b32 s1, v15, 32
	v_mov_b32_e32 v32, s2
	v_mov_b32_e32 v33, s3
	v_pk_add_f32 v[32:33], s[0:1], v[32:33]
	s_nop 0
	v_add_f32_e32 v15, v32, v33
	v_fmamk_f32 v15, v15, 0x3a800000, v66
	v_mul_f32_e32 v17, 0x4b800000, v15
	v_cmp_gt_f32_e64 s[0:1], s44, v15
	s_nop 1
	v_cndmask_b32_e64 v15, v15, v17, s[0:1]
	v_rsq_f32_e32 v15, v15
	s_nop 0
	v_mul_f32_e32 v17, 0x45800000, v15
	v_cndmask_b32_e64 v70, v15, v17, s[0:1]
	v_pk_mul_f32 v[32:33], v[70:71], v[58:59] op_sel_hi:[0,1]
	v_pk_mul_f32 v[58:59], v[70:71], v[60:61] op_sel_hi:[0,1]
	v_cmp_gt_i32_e64 s[0:1], s37, v69
	s_waitcnt vmcnt(0) lgkmcnt(0)
	v_mov_b32_e32 v61, v48
	v_mov_b32_e32 v48, v47
	v_mov_b32_e32 v60, v46
	v_pk_mul_f32 v[46:47], v[48:49], v[58:59]
	v_mov_b32_e32 v48, v50
	v_mov_b32_e32 v49, v52
	v_mov_b32_e32 v52, v51
	v_pk_mul_f32 v[32:33], v[60:61], v[32:33]
	v_mov_b32_e32 v58, v54
	v_mov_b32_e32 v59, v56
	v_mov_b32_e32 v56, v55
	v_pk_add_f32 v[48:49], v[48:49], 1.0 op_sel_hi:[1,0]
	v_pk_add_f32 v[50:51], v[52:53], 1.0 op_sel_hi:[1,0]
	v_pk_fma_f32 v[32:33], v[48:49], v[32:33], v[58:59]
	v_pk_fma_f32 v[46:47], v[50:51], v[46:47], v[56:57]
	v_and_b32_sdwa v17, v32, v67 dst_sel:DWORD dst_unused:UNUSED_PAD src0_sel:WORD_1 src1_sel:DWORD
	v_and_b32_sdwa v19, v47, v67 dst_sel:DWORD dst_unused:UNUSED_PAD src0_sel:WORD_1 src1_sel:DWORD
	v_and_b32_sdwa v48, v46, v67 dst_sel:DWORD dst_unused:UNUSED_PAD src0_sel:WORD_1 src1_sel:DWORD
	v_and_b32_sdwa v15, v33, v67 dst_sel:DWORD dst_unused:UNUSED_PAD src0_sel:WORD_1 src1_sel:DWORD
	v_add3_u32 v17, v32, v17, s42
	v_add3_u32 v19, v47, v19, s42
	v_add3_u32 v32, v46, v48, s42
	v_add3_u32 v15, v33, v15, s42
	v_and_b32_e32 v19, 0xffff0000, v19
	v_and_b32_e32 v32, 0xffff0000, v32
	v_or_b32_sdwa v33, v19, v15 dst_sel:DWORD dst_unused:UNUSED_PAD src0_sel:DWORD src1_sel:WORD_1
	v_or_b32_sdwa v32, v32, v17 dst_sel:DWORD dst_unused:UNUSED_PAD src0_sel:DWORD src1_sel:WORD_1
	v_lshl_add_u64 v[54:55], v[10:11], 0, v[30:31]
	v_mov_b32_e32 v15, v1
	global_store_dwordx2 v[54:55], v[32:33], off
	v_lshl_add_u64 v[46:47], v[42:43], 0, v[14:15]
	v_lshl_add_u64 v[50:51], v[40:41], 0, v[14:15]
	v_pk_mul_f32 v[56:57], v[70:71], v[62:63] op_sel_hi:[0,1]
	v_pk_mul_f32 v[58:59], v[70:71], v[64:65] op_sel_hi:[0,1]
	v_mov_b32_e32 v17, v1
	s_waitcnt lgkmcnt(0)
	v_mov_b32_e32 v30, v100
	v_mov_b32_e32 v31, v101
	v_mov_b32_e32 v32, v102
	v_mov_b32_e32 v33, v103
	v_mov_b32_e32 v46, v104
	v_mov_b32_e32 v47, v105
	v_mov_b32_e32 v48, v106
	v_mov_b32_e32 v49, v107
	v_mov_b32_e32 v50, v108
	v_mov_b32_e32 v51, v109
	v_mov_b32_e32 v52, v110
	v_mov_b32_e32 v53, v111
	v_mov_b32_e32 v60, v30
	v_mov_b32_e32 v61, v32
	v_mov_b32_e32 v62, v46
	v_mov_b32_e32 v63, v48
	v_mov_b32_e32 v32, v31
	v_mov_b32_e32 v48, v47
	v_mov_b32_e32 v64, v50
	v_mov_b32_e32 v65, v52
	v_mov_b32_e32 v52, v51
	v_pk_mul_f32 v[30:31], v[56:57], v[60:61]
	v_pk_add_f32 v[46:47], v[62:63], 1.0 op_sel_hi:[1,0]
	v_pk_mul_f32 v[32:33], v[58:59], v[32:33]
	v_pk_add_f32 v[48:49], v[48:49], 1.0 op_sel_hi:[1,0]
	v_pk_fma_f32 v[30:31], v[30:31], v[46:47], v[64:65]
	v_pk_fma_f32 v[32:33], v[32:33], v[48:49], v[52:53]
	v_and_b32_sdwa v19, v31, v67 dst_sel:DWORD dst_unused:UNUSED_PAD src0_sel:WORD_1 src1_sel:DWORD
	v_and_b32_sdwa v47, v33, v67 dst_sel:DWORD dst_unused:UNUSED_PAD src0_sel:WORD_1 src1_sel:DWORD
	v_and_b32_sdwa v48, v32, v67 dst_sel:DWORD dst_unused:UNUSED_PAD src0_sel:WORD_1 src1_sel:DWORD
	v_and_b32_sdwa v46, v30, v67 dst_sel:DWORD dst_unused:UNUSED_PAD src0_sel:WORD_1 src1_sel:DWORD
	v_add3_u32 v19, v31, v19, s42
	v_add3_u32 v31, v33, v47, s42
	v_add3_u32 v32, v32, v48, s42
	v_add3_u32 v30, v30, v46, s42
	v_and_b32_e32 v31, 0xffff0000, v31
	v_and_b32_e32 v32, 0xffff0000, v32
	v_or_b32_sdwa v31, v31, v19 dst_sel:DWORD dst_unused:UNUSED_PAD src0_sel:DWORD src1_sel:WORD_1
	v_or_b32_sdwa v30, v32, v30 dst_sel:DWORD dst_unused:UNUSED_PAD src0_sel:DWORD src1_sel:WORD_1
	global_store_dwordx2 v[54:55], v[30:31], off offset:512
	v_lshl_add_u64 v[46:47], v[42:43], 0, v[16:17]
	v_lshl_add_u64 v[50:51], v[40:41], 0, v[16:17]
	v_mov_b32_e32 v58, v36
	v_mov_b32_e32 v59, v34
	v_mov_b32_e32 v56, v44
	v_mov_b32_e32 v57, v38
	v_pk_mul_f32 v[58:59], v[70:71], v[58:59] op_sel_hi:[0,1]
	v_pk_mul_f32 v[56:57], v[70:71], v[56:57] op_sel_hi:[0,1]
	v_mov_b32_e32 v19, v1
	v_lshl_add_u64 v[42:43], v[42:43], 0, v[18:19]
	v_lshl_add_u64 v[40:41], v[40:41], 0, v[18:19]
	s_waitcnt lgkmcnt(0)
	v_mov_b32_e32 v30, v112
	v_mov_b32_e32 v31, v113
	v_mov_b32_e32 v32, v114
	v_mov_b32_e32 v33, v115
	v_mov_b32_e32 v46, v116
	v_mov_b32_e32 v47, v117
	v_mov_b32_e32 v48, v118
	v_mov_b32_e32 v49, v119
	v_mov_b32_e32 v50, v120
	v_mov_b32_e32 v51, v121
	v_mov_b32_e32 v52, v122
	v_mov_b32_e32 v53, v123
	v_mov_b32_e32 v61, v32
	v_mov_b32_e32 v32, v31
	v_mov_b32_e32 v63, v48
	v_mov_b32_e32 v48, v47
	v_mov_b32_e32 v60, v30
	v_mov_b32_e32 v62, v46
	v_mov_b32_e32 v65, v52
	v_mov_b32_e32 v52, v51
	v_pk_mul_f32 v[32:33], v[58:59], v[32:33]
	v_pk_add_f32 v[48:49], v[48:49], 1.0 op_sel_hi:[1,0]
	v_mov_b32_e32 v64, v50
	v_pk_mul_f32 v[30:31], v[56:57], v[60:61]
	v_pk_add_f32 v[46:47], v[62:63], 1.0 op_sel_hi:[1,0]
	v_pk_fma_f32 v[32:33], v[32:33], v[48:49], v[52:53]
	v_pk_fma_f32 v[30:31], v[30:31], v[46:47], v[64:65]
	v_and_b32_sdwa v38, v33, v67 dst_sel:DWORD dst_unused:UNUSED_PAD src0_sel:WORD_1 src1_sel:DWORD
	v_and_b32_sdwa v44, v32, v67 dst_sel:DWORD dst_unused:UNUSED_PAD src0_sel:WORD_1 src1_sel:DWORD
	v_and_b32_sdwa v34, v31, v67 dst_sel:DWORD dst_unused:UNUSED_PAD src0_sel:WORD_1 src1_sel:DWORD
	v_and_b32_sdwa v36, v30, v67 dst_sel:DWORD dst_unused:UNUSED_PAD src0_sel:WORD_1 src1_sel:DWORD
	v_add3_u32 v33, v33, v38, s42
	v_add3_u32 v32, v32, v44, s42
	v_add3_u32 v30, v30, v36, s42
	v_add3_u32 v31, v31, v34, s42
	v_and_b32_e32 v33, 0xffff0000, v33
	v_and_b32_e32 v32, 0xffff0000, v32
	v_or_b32_sdwa v31, v33, v31 dst_sel:DWORD dst_unused:UNUSED_PAD src0_sel:DWORD src1_sel:WORD_1
	v_or_b32_sdwa v30, v32, v30 dst_sel:DWORD dst_unused:UNUSED_PAD src0_sel:DWORD src1_sel:WORD_1
	global_store_dwordx2 v[54:55], v[30:31], off offset:1024
	v_mov_b32_e32 v38, v45
	v_mov_b32_e32 v34, v37
	v_pk_mul_f32 v[36:37], v[70:71], v[38:39] op_sel_hi:[0,1]
	v_pk_mul_f32 v[34:35], v[70:71], v[34:35] op_sel_hi:[0,1]
	s_waitcnt lgkmcnt(0)
	v_mov_b32_e32 v30, v124
	v_mov_b32_e32 v31, v125
	v_mov_b32_e32 v32, v126
	v_mov_b32_e32 v33, v127
	v_mov_b32_e32 v46, v128
	v_mov_b32_e32 v47, v129
	v_mov_b32_e32 v48, v130
	v_mov_b32_e32 v49, v131
	v_mov_b32_e32 v40, v132
	v_mov_b32_e32 v41, v133
	v_mov_b32_e32 v42, v134
	v_mov_b32_e32 v43, v135
	v_mov_b32_e32 v39, v32
	v_mov_b32_e32 v32, v31
	v_mov_b32_e32 v45, v48
	v_mov_b32_e32 v48, v47
	v_mov_b32_e32 v38, v30
	v_mov_b32_e32 v44, v46
	v_mov_b32_e32 v51, v42
	v_mov_b32_e32 v42, v41
	v_pk_mul_f32 v[32:33], v[34:35], v[32:33]
	v_pk_add_f32 v[34:35], v[48:49], 1.0 op_sel_hi:[1,0]
	v_mov_b32_e32 v50, v40
	v_pk_mul_f32 v[30:31], v[36:37], v[38:39]
	v_pk_add_f32 v[36:37], v[44:45], 1.0 op_sel_hi:[1,0]
	v_pk_fma_f32 v[32:33], v[32:33], v[34:35], v[42:43]
	v_pk_fma_f32 v[30:31], v[30:31], v[36:37], v[50:51]
	v_and_b32_sdwa v36, v33, v67 dst_sel:DWORD dst_unused:UNUSED_PAD src0_sel:WORD_1 src1_sel:DWORD
	v_and_b32_sdwa v37, v32, v67 dst_sel:DWORD dst_unused:UNUSED_PAD src0_sel:WORD_1 src1_sel:DWORD
	v_and_b32_sdwa v34, v31, v67 dst_sel:DWORD dst_unused:UNUSED_PAD src0_sel:WORD_1 src1_sel:DWORD
	v_and_b32_sdwa v35, v30, v67 dst_sel:DWORD dst_unused:UNUSED_PAD src0_sel:WORD_1 src1_sel:DWORD
	v_add3_u32 v33, v33, v36, s42
	v_add3_u32 v32, v32, v37, s42
	v_add3_u32 v30, v30, v35, s42
	v_add3_u32 v31, v31, v34, s42
	v_and_b32_e32 v33, 0xffff0000, v33
	v_and_b32_e32 v32, 0xffff0000, v32
	v_or_b32_sdwa v31, v33, v31 dst_sel:DWORD dst_unused:UNUSED_PAD src0_sel:DWORD src1_sel:WORD_1
	v_or_b32_sdwa v30, v32, v30 dst_sel:DWORD dst_unused:UNUSED_PAD src0_sel:DWORD src1_sel:WORD_1
	global_store_dwordx2 v[54:55], v[30:31], off offset:1536
	s_and_b64 exec, exec, s[0:1]
	s_cbranch_execz .LBB0_1888
	v_cndmask_b32_e64 v21, v21, 16, vcc
	v_mul_hi_i32_i24_e32 v35, 0x6000, v21
	v_mul_i32_i24_e32 v34, 0x6000, v21
	v_lshl_add_u64 v[34:35], s[12:13], 0, v[34:35]
	v_lshl_add_u64 v[42:43], v[34:35], 0, s[18:19]
	global_load_dwordx4 v[30:33], v[2:3], off
	v_lshl_add_u64 v[44:45], v[34:35], 0, s[20:21]
	v_lshl_add_u64 v[34:35], v[42:43], 0, v[0:1]
	global_load_dwordx4 v[34:37], v[34:35], off
	v_lshl_add_u64 v[38:39], v[44:45], 0, v[0:1]
	global_load_dwordx4 v[38:41], v[38:39], off
	global_load_dwordx4 v[100:103], v[4:5], off
	v_mov_b32_e32 v136, v14
	v_mov_b32_e32 v137, v1
	v_lshl_add_u64 v[138:139], v[42:43], 0, v[136:137]
	global_load_dwordx4 v[104:107], v[138:139], off
	v_mov_b32_e32 v136, v14
	v_mov_b32_e32 v137, v1
	v_lshl_add_u64 v[138:139], v[44:45], 0, v[136:137]
	global_load_dwordx4 v[108:111], v[138:139], off
	global_load_dwordx4 v[112:115], v[6:7], off
	v_mov_b32_e32 v136, v16
	v_mov_b32_e32 v137, v1
	v_lshl_add_u64 v[138:139], v[42:43], 0, v[136:137]
	global_load_dwordx4 v[116:119], v[138:139], off
	v_mov_b32_e32 v136, v16
	v_mov_b32_e32 v137, v1
	v_lshl_add_u64 v[138:139], v[44:45], 0, v[136:137]
	global_load_dwordx4 v[120:123], v[138:139], off
	global_load_dwordx4 v[124:127], v[8:9], off
	v_mov_b32_e32 v136, v18
	v_mov_b32_e32 v137, v1
	v_lshl_add_u64 v[138:139], v[42:43], 0, v[136:137]
	global_load_dwordx4 v[128:131], v[138:139], off
	v_mov_b32_e32 v136, v18
	v_mov_b32_e32 v137, v1
	v_lshl_add_u64 v[138:139], v[44:45], 0, v[136:137]
	global_load_dwordx4 v[132:135], v[138:139], off
	v_lshlrev_b32_e32 v46, 16, v28
	v_and_b32_e32 v28, 0xffff0000, v28
	v_and_b32_e32 v50, 0xffff0000, v26
	v_lshlrev_b32_e32 v48, 16, v26
	v_lshlrev_b32_e32 v53, 16, v24
	v_and_b32_e32 v55, 0xffff0000, v24
	v_lshlrev_b32_e32 v57, 16, v25
	v_and_b32_e32 v59, 0xffff0000, v25
	v_mov_b32_e32 v24, v28
	v_mov_b32_e32 v25, v50
	v_lshlrev_b32_e32 v47, 16, v29
	v_lshlrev_b32_e32 v49, 16, v27
	v_lshlrev_b32_e32 v52, 16, v22
	v_and_b32_e32 v54, 0xffff0000, v22
	v_lshlrev_b32_e32 v56, 16, v23
	v_and_b32_e32 v58, 0xffff0000, v23
	v_mov_b32_e32 v22, v46
	v_mov_b32_e32 v23, v48
	v_pk_mul_f32 v[24:25], v[24:25], v[24:25]
	v_and_b32_e32 v29, 0xffff0000, v29
	v_and_b32_e32 v51, 0xffff0000, v27
	v_mov_b32_e32 v26, v47
	v_mov_b32_e32 v27, v49
	v_pk_mul_f32 v[62:63], v[54:55], v[54:55]
	v_pk_fma_f32 v[22:23], v[22:23], v[22:23], v[24:25]
	v_mov_b32_e32 v60, v29
	v_mov_b32_e32 v61, v51
	v_pk_fma_f32 v[62:63], v[52:53], v[52:53], v[62:63]
	v_pk_fma_f32 v[22:23], v[26:27], v[26:27], v[22:23]
	v_pk_fma_f32 v[24:25], v[56:57], v[56:57], v[62:63]
	v_pk_fma_f32 v[22:23], v[60:61], v[60:61], v[22:23]
	v_pk_fma_f32 v[24:25], v[58:59], v[58:59], v[24:25]
	v_add_f32_e32 v21, v22, v23
	v_add_f32_e32 v21, v21, v24
	v_add_f32_e32 v21, v21, v25
	s_waitcnt vmcnt(0) lgkmcnt(0)
	v_mov_b32_e32 v26, v30
	v_add_f32_dpp v21, v21, v21 quad_perm:[1,0,3,2] row_mask:0xf bank_mask:0xf bound_ctrl:1
	v_mov_b32_e32 v27, v32
	v_mov_b32_e32 v32, v31
	v_add_f32_dpp v21, v21, v21 quad_perm:[2,3,0,1] row_mask:0xf bank_mask:0xf bound_ctrl:1
	s_nop 1
	v_add_f32_dpp v21, v21, v21 row_half_mirror row_mask:0xf bank_mask:0xf bound_ctrl:1
	s_nop 1
	v_add_f32_dpp v21, v21, v21 row_mirror row_mask:0xf bank_mask:0xf bound_ctrl:1
	s_nop 0
	v_readlane_b32 s2, v21, 16
	v_readlane_b32 s3, v21, 48
	v_readlane_b32 s0, v21, 0
	v_readlane_b32 s1, v21, 32
	v_mov_b32_e32 v22, s2
	v_mov_b32_e32 v23, s3
	v_pk_add_f32 v[22:23], s[0:1], v[22:23]
	s_nop 0
	v_add_f32_e32 v21, v22, v23
	v_fmamk_f32 v21, v21, 0x3a800000, v66
	v_mul_f32_e32 v22, 0x4b800000, v21
	v_cmp_gt_f32_e32 vcc, s44, v21
	s_nop 1
	v_cndmask_b32_e32 v21, v21, v22, vcc
	v_rsq_f32_e32 v22, v21
	v_ashrrev_i32_e32 v21, 31, v20
	v_lshlrev_b64 v[20:21], 11, v[20:21]
	v_mul_f32_e32 v23, 0x45800000, v22
	v_cndmask_b32_e32 v60, v22, v23, vcc
	v_pk_mul_f32 v[22:23], v[60:61], v[46:47] op_sel_hi:[0,1]
	v_pk_mul_f32 v[24:25], v[60:61], v[28:29] op_sel_hi:[0,1]
	v_pk_mul_f32 v[22:23], v[26:27], v[22:23]
	v_mov_b32_e32 v27, v36
	v_mov_b32_e32 v36, v35
	v_pk_mul_f32 v[24:25], v[32:33], v[24:25]
	v_mov_b32_e32 v26, v34
	v_mov_b32_e32 v29, v40
	v_mov_b32_e32 v40, v39
	v_pk_add_f32 v[30:31], v[36:37], 1.0 op_sel_hi:[1,0]
	v_mov_b32_e32 v28, v38
	v_pk_add_f32 v[26:27], v[26:27], 1.0 op_sel_hi:[1,0]
	v_pk_fma_f32 v[24:25], v[30:31], v[24:25], v[40:41]
	v_pk_fma_f32 v[22:23], v[26:27], v[22:23], v[28:29]
	v_and_b32_sdwa v28, v25, v67 dst_sel:DWORD dst_unused:UNUSED_PAD src0_sel:WORD_1 src1_sel:DWORD
	v_and_b32_sdwa v29, v24, v67 dst_sel:DWORD dst_unused:UNUSED_PAD src0_sel:WORD_1 src1_sel:DWORD
	v_and_b32_sdwa v26, v23, v67 dst_sel:DWORD dst_unused:UNUSED_PAD src0_sel:WORD_1 src1_sel:DWORD
	v_and_b32_sdwa v27, v22, v67 dst_sel:DWORD dst_unused:UNUSED_PAD src0_sel:WORD_1 src1_sel:DWORD
	v_add3_u32 v25, v25, v28, s42
	v_add3_u32 v24, v24, v29, s42
	v_add3_u32 v22, v22, v27, s42
	v_add3_u32 v23, v23, v26, s42
	v_and_b32_e32 v25, 0xffff0000, v25
	v_and_b32_e32 v24, 0xffff0000, v24
	v_or_b32_sdwa v23, v25, v23 dst_sel:DWORD dst_unused:UNUSED_PAD src0_sel:DWORD src1_sel:WORD_1
	v_or_b32_sdwa v22, v24, v22 dst_sel:DWORD dst_unused:UNUSED_PAD src0_sel:DWORD src1_sel:WORD_1
	v_lshl_add_u64 v[32:33], v[10:11], 0, v[20:21]
	global_store_dwordx2 v[32:33], v[22:23], off
	v_lshl_add_u64 v[24:25], v[42:43], 0, v[14:15]
	v_lshl_add_u64 v[28:29], v[44:45], 0, v[14:15]
	v_pk_mul_f32 v[34:35], v[60:61], v[48:49] op_sel_hi:[0,1]
	v_pk_mul_f32 v[36:37], v[60:61], v[50:51] op_sel_hi:[0,1]
	s_waitcnt lgkmcnt(0)
	v_mov_b32_e32 v20, v100
	v_mov_b32_e32 v21, v101
	v_mov_b32_e32 v22, v102
	v_mov_b32_e32 v23, v103
	v_mov_b32_e32 v24, v104
	v_mov_b32_e32 v25, v105
	v_mov_b32_e32 v26, v106
	v_mov_b32_e32 v27, v107
	v_mov_b32_e32 v28, v108
	v_mov_b32_e32 v29, v109
	v_mov_b32_e32 v30, v110
	v_mov_b32_e32 v31, v111
	v_mov_b32_e32 v38, v20
	v_mov_b32_e32 v39, v22
	v_mov_b32_e32 v40, v24
	v_mov_b32_e32 v41, v26
	v_mov_b32_e32 v22, v21
	v_mov_b32_e32 v26, v25
	v_mov_b32_e32 v46, v28
	v_mov_b32_e32 v47, v30
	v_mov_b32_e32 v30, v29
	v_pk_mul_f32 v[20:21], v[34:35], v[38:39]
	v_pk_add_f32 v[24:25], v[40:41], 1.0 op_sel_hi:[1,0]
	v_pk_mul_f32 v[22:23], v[36:37], v[22:23]
	v_pk_add_f32 v[26:27], v[26:27], 1.0 op_sel_hi:[1,0]
	v_pk_fma_f32 v[20:21], v[20:21], v[24:25], v[46:47]
	v_pk_fma_f32 v[22:23], v[22:23], v[26:27], v[30:31]
	v_and_b32_sdwa v15, v21, v67 dst_sel:DWORD dst_unused:UNUSED_PAD src0_sel:WORD_1 src1_sel:DWORD
	v_and_b32_sdwa v25, v23, v67 dst_sel:DWORD dst_unused:UNUSED_PAD src0_sel:WORD_1 src1_sel:DWORD
	v_and_b32_sdwa v26, v22, v67 dst_sel:DWORD dst_unused:UNUSED_PAD src0_sel:WORD_1 src1_sel:DWORD
	v_and_b32_sdwa v24, v20, v67 dst_sel:DWORD dst_unused:UNUSED_PAD src0_sel:WORD_1 src1_sel:DWORD
	v_add3_u32 v15, v21, v15, s42
	v_add3_u32 v21, v23, v25, s42
	v_add3_u32 v22, v22, v26, s42
	v_add3_u32 v20, v20, v24, s42
	v_and_b32_e32 v21, 0xffff0000, v21
	v_and_b32_e32 v22, 0xffff0000, v22
	v_or_b32_sdwa v21, v21, v15 dst_sel:DWORD dst_unused:UNUSED_PAD src0_sel:DWORD src1_sel:WORD_1
	v_or_b32_sdwa v20, v22, v20 dst_sel:DWORD dst_unused:UNUSED_PAD src0_sel:DWORD src1_sel:WORD_1
	global_store_dwordx2 v[32:33], v[20:21], off offset:512
	v_lshl_add_u64 v[24:25], v[42:43], 0, v[16:17]
	v_lshl_add_u64 v[28:29], v[44:45], 0, v[16:17]
	v_mov_b32_e32 v34, v52
	v_mov_b32_e32 v35, v56
	v_mov_b32_e32 v36, v54
	v_mov_b32_e32 v37, v58
	v_pk_mul_f32 v[34:35], v[60:61], v[34:35] op_sel_hi:[0,1]
	v_pk_mul_f32 v[36:37], v[60:61], v[36:37] op_sel_hi:[0,1]
	v_mov_b32_e32 v56, v53
	v_mov_b32_e32 v58, v55
	s_waitcnt lgkmcnt(0)
	v_mov_b32_e32 v20, v112
	v_mov_b32_e32 v21, v113
	v_mov_b32_e32 v22, v114
	v_mov_b32_e32 v23, v115
	v_mov_b32_e32 v24, v116
	v_mov_b32_e32 v25, v117
	v_mov_b32_e32 v26, v118
	v_mov_b32_e32 v27, v119
	v_mov_b32_e32 v28, v120
	v_mov_b32_e32 v29, v121
	v_mov_b32_e32 v30, v122
	v_mov_b32_e32 v31, v123
	v_mov_b32_e32 v38, v20
	v_mov_b32_e32 v39, v22
	v_mov_b32_e32 v40, v24
	v_mov_b32_e32 v41, v26
	v_mov_b32_e32 v22, v21
	v_mov_b32_e32 v26, v25
	v_mov_b32_e32 v46, v28
	v_mov_b32_e32 v47, v30
	v_mov_b32_e32 v30, v29
	v_pk_mul_f32 v[20:21], v[34:35], v[38:39]
	v_pk_add_f32 v[24:25], v[40:41], 1.0 op_sel_hi:[1,0]
	v_pk_mul_f32 v[22:23], v[36:37], v[22:23]
	v_pk_add_f32 v[26:27], v[26:27], 1.0 op_sel_hi:[1,0]
	v_pk_fma_f32 v[20:21], v[20:21], v[24:25], v[46:47]
	v_pk_fma_f32 v[22:23], v[22:23], v[26:27], v[30:31]
	v_and_b32_sdwa v15, v21, v67 dst_sel:DWORD dst_unused:UNUSED_PAD src0_sel:WORD_1 src1_sel:DWORD
	v_and_b32_sdwa v17, v20, v67 dst_sel:DWORD dst_unused:UNUSED_PAD src0_sel:WORD_1 src1_sel:DWORD
	v_and_b32_sdwa v24, v23, v67 dst_sel:DWORD dst_unused:UNUSED_PAD src0_sel:WORD_1 src1_sel:DWORD
	v_and_b32_sdwa v25, v22, v67 dst_sel:DWORD dst_unused:UNUSED_PAD src0_sel:WORD_1 src1_sel:DWORD
	v_add3_u32 v17, v20, v17, s42
	v_add3_u32 v15, v21, v15, s42
	v_add3_u32 v20, v23, v24, s42
	v_add3_u32 v21, v22, v25, s42
	v_and_b32_e32 v20, 0xffff0000, v20
	v_and_b32_e32 v22, 0xffff0000, v21
	v_or_b32_sdwa v21, v20, v15 dst_sel:DWORD dst_unused:UNUSED_PAD src0_sel:DWORD src1_sel:WORD_1
	v_or_b32_sdwa v20, v22, v17 dst_sel:DWORD dst_unused:UNUSED_PAD src0_sel:DWORD src1_sel:WORD_1
	global_store_dwordx2 v[32:33], v[20:21], off offset:1024
	v_lshl_add_u64 v[24:25], v[42:43], 0, v[18:19]
	v_lshl_add_u64 v[28:29], v[44:45], 0, v[18:19]
	v_pk_mul_f32 v[34:35], v[60:61], v[56:57] op_sel_hi:[0,1]
	v_pk_mul_f32 v[36:37], v[60:61], v[58:59] op_sel_hi:[0,1]
	s_waitcnt lgkmcnt(0)
	v_mov_b32_e32 v20, v124
	v_mov_b32_e32 v21, v125
	v_mov_b32_e32 v22, v126
	v_mov_b32_e32 v23, v127
	v_mov_b32_e32 v24, v128
	v_mov_b32_e32 v25, v129
	v_mov_b32_e32 v26, v130
	v_mov_b32_e32 v27, v131
	v_mov_b32_e32 v28, v132
	v_mov_b32_e32 v29, v133
	v_mov_b32_e32 v30, v134
	v_mov_b32_e32 v31, v135
	v_mov_b32_e32 v38, v20
	v_mov_b32_e32 v39, v22
	v_mov_b32_e32 v40, v24
	v_mov_b32_e32 v41, v26
	v_mov_b32_e32 v22, v21
	v_mov_b32_e32 v26, v25
	v_mov_b32_e32 v42, v28
	v_mov_b32_e32 v43, v30
	v_mov_b32_e32 v30, v29
	v_pk_mul_f32 v[20:21], v[34:35], v[38:39]
	v_pk_add_f32 v[24:25], v[40:41], 1.0 op_sel_hi:[1,0]
	v_pk_mul_f32 v[22:23], v[36:37], v[22:23]
	v_pk_add_f32 v[26:27], v[26:27], 1.0 op_sel_hi:[1,0]
	v_pk_fma_f32 v[20:21], v[20:21], v[24:25], v[42:43]
	v_pk_fma_f32 v[22:23], v[22:23], v[26:27], v[30:31]
	v_and_b32_sdwa v17, v20, v67 dst_sel:DWORD dst_unused:UNUSED_PAD src0_sel:WORD_1 src1_sel:DWORD
	v_and_b32_sdwa v19, v23, v67 dst_sel:DWORD dst_unused:UNUSED_PAD src0_sel:WORD_1 src1_sel:DWORD
	v_and_b32_sdwa v24, v22, v67 dst_sel:DWORD dst_unused:UNUSED_PAD src0_sel:WORD_1 src1_sel:DWORD
	v_and_b32_sdwa v15, v21, v67 dst_sel:DWORD dst_unused:UNUSED_PAD src0_sel:WORD_1 src1_sel:DWORD
	v_add3_u32 v17, v20, v17, s42
	v_add3_u32 v19, v23, v19, s42
	v_add3_u32 v20, v22, v24, s42
	v_add3_u32 v15, v21, v15, s42
	v_and_b32_e32 v19, 0xffff0000, v19
	v_and_b32_e32 v20, 0xffff0000, v20
	v_or_b32_sdwa v21, v19, v15 dst_sel:DWORD dst_unused:UNUSED_PAD src0_sel:DWORD src1_sel:WORD_1
	v_or_b32_sdwa v20, v20, v17 dst_sel:DWORD dst_unused:UNUSED_PAD src0_sel:DWORD src1_sel:WORD_1
	global_store_dwordx2 v[32:33], v[20:21], off offset:1536
	s_branch .LBB0_1888
